# chunk-granular late prep with stride gridDim-64 (grid-size general), two-chunk ring barriers
# baseline (speedup 1.0000x reference)
; __global__ void __launch_bounds__(NTHR, 2) hybrid_fwd(Args args) {
;     ...
;         for (int tile = blockIdx.x; tile < T / 32; tile += F.G) p2_rwprep_tile(F, args, tile * 32); }
.Lrw_step:
	s_cmp_eq_u32 s98, 1
	s_cbranch_scc1 .Lrw_step1
	s_add_i32 s56, s56, s97
	s_cmpk_gt_i32 s56, 0xff
	s_cbranch_scc1 .LBB0_347
	s_branch .LBB0_323
.Lrw_step1:
	s_add_i32 s101, s97, -64
	s_add_i32 s99, s99, s101
	s_cmpk_gt_i32 s99, 0x1ff
	s_cbranch_scc1 .LBB0_347
	s_lshr_b32 s56, s99, 1
	s_add_i32 s56, s56, 0x100
